# GEMM phase prologues: K-tile 1 staging loads issued before the first wait/barrier (vmcnt 2 -> 8) in gate-up, down, Q, w_in and output-projection phases
# baseline (speedup 1.0000x reference)
.LBB0_200:
	s_add_u32 s34, s42, 0x18400000
	s_addc_u32 s35, s43, 0
	s_lshl_b64 s[16:17], s[36:37], 2
	s_add_u32 s15, s42, s16
	s_addc_u32 s16, s43, s17
	s_add_u32 s36, s15, 0x10000
	s_addc_u32 s37, s16, 0
	s_lshl_b32 s15, s44, 5
	s_and_b32 s48, s15, 0x60
	s_lshl_b32 s21, s19, 13
	s_lshl_b32 s40, s48, 7
	s_ashr_i32 s15, s4, 31
	s_add_u32 s80, s42, 0x41800000
	s_addc_u32 s49, s43, 0
	s_add_i32 m0, s11, 0x18000
	v_lshl_add_u64 v[8:9], v[8:9], 0, s[30:31]
	global_load_lds_dwordx4 v[8:9], off
	v_lshl_add_u64 v[6:7], v[6:7], 0, s[30:31]
	s_add_i32 m0, s11, 0x1a000
	s_add_i32 s16, s11, 0x8000
	s_add_i32 s17, s11, 0xa000
	global_load_lds_dwordx4 v[6:7], off
	v_lshl_add_u64 v[2:3], v[2:3], 0, s[30:31]
	s_mov_b32 m0, s16
	s_add_u32 s38, s62, 0x80080
	global_load_lds_dwordx4 v[2:3], off
	v_lshl_add_u64 v[2:3], v[4:5], 0, s[30:31]
	s_mov_b32 m0, s17
	s_addc_u32 s39, s63, 0
	global_load_lds_dwordx4 v[2:3], off
	s_add_i32 m0, s11, 0x1c000
	v_lshl_add_u64 v[2:3], s[38:39], 0, v[66:67]
	global_load_lds_dwordx4 v[2:3], off
	v_lshl_add_u64 v[2:3], s[38:39], 0, v[136:137]
	s_add_i32 m0, s11, 0x1e000
	v_lshrrev_b32_e32 v4, 1, v10
	global_load_lds_dwordx4 v[2:3], off
	v_and_b32_e32 v4, 24, v4
	v_and_b32_e32 v3, 15, v10
	v_lshlrev_b32_e32 v5, 1, v4
	v_lshl_or_b32 v154, s19, 6, v3
	v_lshl_or_b32 v3, v3, 6, v5
	v_lshlrev_b32_e32 v5, 2, v10
	v_and_b32_e32 v2, 63, v10
	v_and_b32_e32 v5, 32, v5
	s_cmpk_lt_u32 s18, 0x100
	v_bitop3_b32 v156, v3, s40, v5 bitop3:0xde
	s_cselect_b64 s[40:41], -1, 0
	v_cmp_eq_u32_e64 s[38:39], 0, v2
	s_ashr_i32 s45, s44, 31
	v_lshlrev_b32_e32 v2, 4, v2
	s_lshl_b64 s[46:47], s[44:45], 14
	v_lshl_or_b32 v161, s44, 14, v2
	s_lshl_b64 s[44:45], s[44:45], 2
	s_add_u32 s19, s42, s44
	v_bitop3_b32 v155, v3, s21, v5 bitop3:0xde
	s_addc_u32 s21, s43, s45
	s_add_u32 s19, s19, 0x80000
	s_addc_u32 s55, s21, 0
	s_and_b32 s81, s49, 0xffff
	s_add_u32 s42, s80, s46
	s_addc_u32 s43, s49, s47
	v_mov_b32_e32 v3, v67
	v_lshl_add_u64 v[138:139], s[42:43], 0, v[2:3]
	v_lshlrev_b32_e32 v2, 15, v11
	v_and_b32_e32 v2, 0xffff0000, v2
	v_lshl_add_u32 v2, v12, 12, v2
	v_and_b32_e32 v3, 1, v11
	v_lshl_or_b32 v2, v3, 6, v2
	v_lshl_add_u32 v140, v13, 1, v2
	v_lshlrev_b32_e32 v2, 15, v14
	v_and_b32_e32 v2, 0xffff0000, v2
	s_waitcnt vmcnt(8)
	s_barrier
	s_waitcnt vmcnt(6)
	v_lshl_add_u32 v2, v15, 12, v2
	v_and_b32_e32 v3, 1, v14
	v_lshl_or_b32 v2, v3, 6, v2
	s_mov_b32 s18, 0
	v_or_b32_e32 v157, 16, v154
	v_or_b32_e32 v158, 32, v154
	v_or_b32_e32 v159, 48, v154
	v_add_u32_e32 v160, 0xb0, v154
	v_or_b32_e32 v162, s48, v4
	v_mov_b32_e32 v141, v67
	v_lshl_add_u32 v142, v16, 1, v2
	v_mov_b32_e32 v143, v67
	s_barrier
	s_branch .LBB0_203

.LBB0_321:
	s_add_u32 s50, s42, 0x14200000
	s_addc_u32 s51, s43, 0
	s_lshl_b64 s[14:15], s[34:35], 2
	s_add_u32 s12, s42, s14
	s_addc_u32 s14, s43, s15
	s_add_u32 s52, s12, 0x10000
	s_addc_u32 s53, s14, 0
	s_cmp_eq_u32 s76, 3
	s_cselect_b64 s[54:55], -1, 0
	s_cmp_lg_u32 s76, 3
	s_cselect_b64 s[56:57], -1, 0
	s_add_u32 s58, s0, 0x8000000
	v_and_b32_e32 v19, 63, v10
	v_and_b32_e32 v234, 15, v10
	v_lshrrev_b32_e32 v20, 1, v10
	v_and_b32_e32 v21, 48, v10
	v_lshlrev_b32_e32 v10, 2, v10
	s_addc_u32 s59, s1, 0
	s_and_b32 s12, s48, 3
	s_lshl_b32 s85, s10, 6
	s_lshl_b32 s10, s10, 13
	v_lshl_or_b32 v21, v234, 6, v21
	v_and_b32_e32 v10, 32, v10
	v_bitop3_b32 v236, v21, s10, v10 bitop3:0xde
	s_lshl_b32 s10, s12, 12
	s_ashr_i32 s87, s4, 31
	s_add_u32 s80, s42, 0x41800000
	v_bitop3_b32 v237, v21, s10, v10 bitop3:0xde
	s_addc_u32 s10, s43, 0
	s_add_i32 m0, s77, 0x18000
	v_lshl_add_u64 v[8:9], v[8:9], 0, s[30:31]
	global_load_lds_dwordx4 v[8:9], off
	v_lshl_add_u64 v[6:7], v[6:7], 0, s[30:31]
	s_add_i32 m0, s77, 0x1a000
	s_add_i32 s88, s77, 0x8000
	s_add_i32 s89, s77, 0xa000
	global_load_lds_dwordx4 v[6:7], off
	v_lshl_add_u64 v[2:3], v[2:3], 0, s[30:31]
	s_mov_b32 m0, s88
	s_add_u32 s14, s46, 0x160080
	global_load_lds_dwordx4 v[2:3], off
	v_lshl_add_u64 v[2:3], v[4:5], 0, s[30:31]
	s_mov_b32 m0, s89
	s_addc_u32 s15, s47, 0
	global_load_lds_dwordx4 v[2:3], off
	s_add_i32 m0, s77, 0x1c000
	v_lshl_add_u64 v[2:3], s[14:15], 0, v[202:203]
	global_load_lds_dwordx4 v[2:3], off
	v_lshl_add_u64 v[2:3], s[14:15], 0, v[206:207]
	s_add_i32 m0, s77, 0x1e000
	s_cmpk_lt_u32 s8, 0x100
	global_load_lds_dwordx4 v[2:3], off
	s_cselect_b64 s[34:35], -1, 0
	s_ashr_i32 s49, s48, 31
	s_lshl_b64 s[14:15], s[48:49], 14
	s_lshl_b32 s12, s12, 6
	s_lshl_b64 s[18:19], s[48:49], 2
	s_add_u32 s16, s42, s18
	s_addc_u32 s18, s43, s19
	s_add_u32 s16, s16, 0x80000
	v_writelane_b32 v255, s16, 25
	s_addc_u32 s16, s18, 0
	s_and_b32 s81, s10, 0xffff
	s_add_u32 s14, s80, s14
	v_and_or_b32 v242, v20, 24, s12
	s_movk_i32 s12, 0x1600
	v_lshlrev_b32_e32 v66, 4, v19
	s_addc_u32 s15, s10, s15
	v_lshrrev_b32_e32 v3, 1, v11
	v_mul_lo_u32 v2, v13, s12
	s_mov_b32 s10, 0x16000
	v_lshl_add_u64 v[208:209], s[14:15], 0, v[66:67]
	v_mad_u64_u32 v[2:3], s[14:15], v3, s10, v[2:3]
	v_or_b32_e32 v2, v2, v12
	v_lshl_or_b32 v241, s48, 14, v66
	v_add_lshl_u32 v66, v2, v14, 1
	v_lshrrev_b32_e32 v3, 1, v15
	v_mul_lo_u32 v2, v17, s12
	v_mad_u64_u32 v[2:3], s[14:15], v3, s10, v[2:3]
	s_waitcnt vmcnt(8)
	s_barrier
	s_waitcnt vmcnt(6)
	s_mov_b64 s[18:19], 0x160080
	v_or_b32_e32 v2, v2, v16
	v_or_b32_e32 v235, s85, v234
	v_lshl_add_u64 v[210:211], v[66:67], 0, s[18:19]
	v_add_lshl_u32 v66, v2, v18, 1
	s_mov_b32 s8, 0
	v_cmp_eq_u32_e64 s[38:39], 0, v19
	v_cmp_gt_u32_e64 s[40:41], 16, v19
	v_or_b32_e32 v238, 16, v235
	v_or_b32_e32 v239, 32, v235
	v_or_b32_e32 v240, 48, v235
	v_writelane_b32 v255, s16, 27
	v_lshl_add_u64 v[212:213], v[66:67], 0, s[18:19]
	v_lshl_add_u64 v[214:215], v[204:205], 0, s[18:19]
	s_barrier
	s_branch .LBB0_324

.LBB0_707:
	s_add_u32 s80, s48, 0x41800000
	s_addc_u32 s23, s49, 0
	s_add_u32 s36, s48, 0x52000
	v_lshrrev_b32_e32 v19, 1, v10
	s_addc_u32 s37, s49, 0
	v_and_b32_e32 v19, 24, v19
	s_add_u32 s42, s48, 0x24a00000
	v_and_b32_e32 v17, 63, v10
	v_and_b32_e32 v18, 15, v10
	v_lshlrev_b32_e32 v20, 1, v19
	v_lshlrev_b32_e32 v10, 2, v10
	s_addc_u32 s43, s49, 0
	s_and_b32 s24, s50, 3
	v_lshl_or_b32 v202, s14, 6, v18
	v_lshl_or_b32 v18, v18, 6, v20
	s_lshl_b32 s14, s14, 13
	v_and_b32_e32 v10, 32, v10
	v_bitop3_b32 v203, v18, s14, v10 bitop3:0xde
	s_lshl_b32 s14, s24, 12
	s_add_i32 m0, s10, 0x18000
	v_lshl_add_u64 v[8:9], v[8:9], 0, s[30:31]
	v_bitop3_b32 v204, v18, s14, v10 bitop3:0xde
	global_load_lds_dwordx4 v[8:9], off
	v_lshl_add_u64 v[6:7], v[6:7], 0, s[30:31]
	s_add_i32 m0, s10, 0x1a000
	s_add_i32 s14, s10, 0x8000
	s_add_i32 s15, s10, 0xa000
	global_load_lds_dwordx4 v[6:7], off
	v_lshl_add_u64 v[2:3], v[2:3], 0, s[30:31]
	s_mov_b32 m0, s14
	s_add_u32 s18, s64, 0x80080
	global_load_lds_dwordx4 v[2:3], off
	v_lshl_add_u64 v[2:3], v[4:5], 0, s[30:31]
	s_mov_b32 m0, s15
	s_addc_u32 s19, s65, 0
	global_load_lds_dwordx4 v[2:3], off
	s_add_i32 m0, s10, 0x1c000
	v_lshl_add_u64 v[2:3], s[18:19], 0, v[66:67]
	global_load_lds_dwordx4 v[2:3], off
	v_lshl_add_u64 v[2:3], s[18:19], 0, v[168:169]
	s_add_i32 m0, s10, 0x1e000
	s_cmpk_lt_u32 s16, 0x100
	global_load_lds_dwordx4 v[2:3], off
	s_cselect_b64 s[44:45], -1, 0
	s_ashr_i32 s51, s50, 31
	s_lshl_b64 s[16:17], s[50:51], 14
	s_lshl_b64 s[18:19], s[50:51], 2
	s_add_u32 s18, s48, s18
	s_addc_u32 s19, s49, s19
	s_add_u32 s61, s18, 0x80000
	s_addc_u32 s72, s19, 0
	s_and_b32 s81, s23, 0xffff
	s_add_u32 s16, s80, s16
	v_lshlrev_b32_e32 v2, 4, v17
	s_addc_u32 s17, s23, s17
	v_mov_b32_e32 v3, v67
	v_lshl_or_b32 v208, s50, 14, v2
	v_lshl_add_u64 v[170:171], s[16:17], 0, v[2:3]
	v_lshlrev_b32_e32 v2, 2, v19
	v_lshl_add_u64 v[172:173], s[46:47], 0, v[2:3]
	v_lshlrev_b32_e32 v2, 15, v11
	v_and_b32_e32 v2, 0xffff0000, v2
	v_lshl_add_u32 v2, v12, 12, v2
	v_and_b32_e32 v3, 1, v11
	v_lshl_or_b32 v2, v3, 6, v2
	v_lshl_add_u32 v174, v13, 1, v2
	v_lshlrev_b32_e32 v2, 15, v14
	v_and_b32_e32 v2, 0xffff0000, v2
	s_waitcnt vmcnt(8)
	s_barrier
	s_waitcnt vmcnt(6)
	v_lshl_add_u32 v2, v15, 12, v2
	v_and_b32_e32 v3, 1, v14
	v_lshl_or_b32 v2, v3, 6, v2
	s_mov_b32 s59, 0
	v_cmp_eq_u32_e64 s[38:39], 0, v17
	v_or_b32_e32 v205, 16, v202
	v_or_b32_e32 v206, 32, v202
	v_or_b32_e32 v207, 48, v202
	v_lshl_or_b32 v209, s24, 6, v19
	v_mov_b32_e32 v175, v67
	v_lshl_add_u32 v176, v16, 1, v2
	v_mov_b32_e32 v177, v67
	s_barrier
	s_branch .LBB0_710

.LBB0_1287:
	s_add_u32 s80, s36, 0x41800000
	s_addc_u32 s6, s37, 0
	s_add_u32 s42, s36, 0x18400000
	s_addc_u32 s43, s37, 0
	s_add_u32 s44, s36, 0x1c600000
	v_lshrrev_b32_e32 v19, 1, v10
	s_addc_u32 s45, s37, 0
	v_and_b32_e32 v19, 24, v19
	s_add_u32 s46, s36, 0x20800
	v_and_b32_e32 v17, 63, v10
	v_and_b32_e32 v18, 15, v10
	v_lshlrev_b32_e32 v20, 1, v19
	v_lshlrev_b32_e32 v10, 2, v10
	s_addc_u32 s47, s37, 0
	s_and_b32 s10, s50, 3
	v_lshl_or_b32 v202, s2, 6, v18
	v_lshl_or_b32 v18, v18, 6, v20
	s_lshl_b32 s2, s2, 13
	v_and_b32_e32 v10, 32, v10
	v_bitop3_b32 v203, v18, s2, v10 bitop3:0xde
	s_lshl_b32 s2, s10, 12
	s_add_i32 m0, s61, 0x18000
	v_lshl_add_u64 v[8:9], v[8:9], 0, s[30:31]
	v_bitop3_b32 v204, v18, s2, v10 bitop3:0xde
	global_load_lds_dwordx4 v[8:9], off
	v_lshl_add_u64 v[6:7], v[6:7], 0, s[30:31]
	s_add_i32 m0, s61, 0x1a000
	s_add_i32 s39, s61, 0x8000
	s_add_i32 s2, s61, 0xa000
	global_load_lds_dwordx4 v[6:7], off
	v_lshl_add_u64 v[2:3], v[2:3], 0, s[30:31]
	s_mov_b32 m0, s39
	s_add_u32 s4, s64, 0x80080
	global_load_lds_dwordx4 v[2:3], off
	v_lshl_add_u64 v[2:3], v[4:5], 0, s[30:31]
	s_mov_b32 m0, s2
	s_addc_u32 s5, s65, 0
	global_load_lds_dwordx4 v[2:3], off
	s_add_i32 m0, s61, 0x1c000
	v_lshl_add_u64 v[2:3], s[4:5], 0, v[166:167]
	global_load_lds_dwordx4 v[2:3], off
	v_lshl_add_u64 v[2:3], s[4:5], 0, v[170:171]
	s_add_i32 m0, s61, 0x1e000
	s_cmpk_lt_u32 s3, 0x100
	global_load_lds_dwordx4 v[2:3], off
	v_cmp_eq_u32_e64 s[4:5], 0, v17
	s_cselect_b64 s[48:49], -1, 0
	s_ashr_i32 s51, s50, 31
	v_writelane_b32 v255, s4, 25
	v_lshlrev_b32_e32 v2, 15, v11
	s_lshl_b64 s[8:9], s[50:51], 2
	v_writelane_b32 v255, s5, 26
	s_lshl_b64 s[4:5], s[50:51], 14
	v_and_b32_e32 v2, 0xffff0000, v2
	s_add_u32 s8, s36, s8
	v_lshl_add_u32 v2, v12, 12, v2
	v_and_b32_e32 v3, 1, v11
	s_addc_u32 s9, s37, s9
	v_lshl_or_b32 v2, v3, 6, v2
	s_add_u32 s8, s8, 0x80000
	v_lshl_add_u32 v174, v13, 1, v2
	v_lshlrev_b32_e32 v2, 15, v14
	v_writelane_b32 v255, s8, 27
	s_addc_u32 s8, s9, 0
	s_and_b32 s81, s6, 0xffff
	v_and_b32_e32 v2, 0xffff0000, v2
	s_waitcnt vmcnt(8)
	s_barrier
	s_waitcnt vmcnt(6)
	s_add_u32 s4, s80, s4
	v_lshl_add_u32 v2, v15, 12, v2
	v_and_b32_e32 v3, 1, v14
	v_lshlrev_b32_e32 v66, 4, v17
	s_addc_u32 s5, s6, s5
	v_lshl_or_b32 v2, v3, 6, v2
	s_mov_b32 s3, 0
	v_or_b32_e32 v205, 16, v202
	v_or_b32_e32 v206, 32, v202
	v_or_b32_e32 v207, 48, v202
	v_add_u32_e32 v208, 0xa0, v202
	v_add_u32_e32 v209, 0xb0, v202
	v_lshl_or_b32 v210, s50, 14, v66
	v_writelane_b32 v255, s8, 33
	v_lshl_add_u64 v[172:173], s[4:5], 0, v[66:67]
	v_lshl_or_b32 v211, s10, 6, v19
	v_mov_b32_e32 v175, v67
	v_lshl_add_u32 v176, v16, 1, v2
	v_mov_b32_e32 v177, v67
	s_barrier
	s_branch .LBB0_1290

.LBB0_2403:
	s_and_b64 s[22:23], s[24:25], exec
	s_mov_b32 s18, 0x21000
	s_cselect_b32 s18, s18, 0x52800
	s_add_u32 s80, s40, 0x41800000
	s_addc_u32 s24, s41, 0
	s_add_u32 s34, s40, 0x14200000
	s_addc_u32 s35, s41, 0
	s_add_u32 s18, s40, s18
	s_addc_u32 s22, s41, 0
	s_add_u32 s36, s18, 0x10000
	v_and_b32_e32 v17, 63, v10
	v_and_b32_e32 v18, 15, v10
	v_lshrrev_b32_e32 v19, 1, v10
	v_and_b32_e32 v20, 48, v10
	v_lshlrev_b32_e32 v10, 2, v10
	s_addc_u32 s37, s22, 0
	s_and_b32 s18, s48, 3
	s_lshl_b32 s25, s17, 6
	s_lshl_b32 s17, s17, 13
	v_lshl_or_b32 v20, v18, 6, v20
	v_and_b32_e32 v10, 32, v10
	s_add_i32 m0, s13, 0x18000
	v_lshl_add_u64 v[8:9], v[8:9], 0, s[30:31]
	v_bitop3_b32 v221, v20, s17, v10 bitop3:0xde
	s_lshl_b32 s17, s18, 12
	global_load_lds_dwordx4 v[8:9], off
	v_lshl_add_u64 v[6:7], v[6:7], 0, s[30:31]
	s_add_i32 m0, s13, 0x1a000
	s_add_i32 s72, s13, 0x8000
	s_add_i32 s73, s13, 0xa000
	global_load_lds_dwordx4 v[6:7], off
	v_lshl_add_u64 v[2:3], v[2:3], 0, s[30:31]
	s_mov_b32 m0, s72
	s_add_u32 s22, s64, 0x80080
	global_load_lds_dwordx4 v[2:3], off
	v_lshl_add_u64 v[2:3], v[4:5], 0, s[30:31]
	s_mov_b32 m0, s73
	s_addc_u32 s23, s65, 0
	global_load_lds_dwordx4 v[2:3], off
	s_add_i32 m0, s13, 0x1c000
	v_lshl_add_u64 v[2:3], s[22:23], 0, v[66:67]
	global_load_lds_dwordx4 v[2:3], off
	v_lshl_add_u64 v[2:3], s[22:23], 0, v[204:205]
	s_add_i32 m0, s13, 0x1e000
	s_cmpk_lt_u32 s16, 0x100
	global_load_lds_dwordx4 v[2:3], off
	s_cselect_b64 s[44:45], -1, 0
	s_ashr_i32 s49, s48, 31
	v_or_b32_e32 v220, s25, v18
	v_bitop3_b32 v222, v20, s17, v10 bitop3:0xde
	s_lshl_b64 s[16:17], s[48:49], 14
	s_lshl_b32 s18, s18, 6
	s_addk_i32 s25, 0x80
	s_lshl_b64 s[22:23], s[48:49], 2
	s_add_u32 s22, s40, s22
	s_addc_u32 s23, s41, s23
	s_add_u32 s74, s22, 0x80000
	s_addc_u32 s77, s23, 0
	s_and_b32 s81, s24, 0xffff
	s_add_u32 s16, s80, s16
	v_lshlrev_b32_e32 v2, 4, v17
	s_addc_u32 s17, s24, s17
	v_mov_b32_e32 v3, v67
	v_lshl_or_b32 v236, s48, 14, v2
	v_lshl_add_u64 v[206:207], s[16:17], 0, v[2:3]
	v_lshlrev_b32_e32 v2, 15, v11
	v_and_b32_e32 v2, 0xffff0000, v2
	v_lshl_add_u32 v2, v12, 12, v2
	v_and_b32_e32 v3, 1, v11
	v_lshl_or_b32 v2, v3, 6, v2
	v_lshl_add_u32 v208, v13, 1, v2
	v_lshlrev_b32_e32 v2, 15, v14
	v_and_b32_e32 v2, 0xffff0000, v2
	s_waitcnt vmcnt(8)
	s_barrier
	s_waitcnt vmcnt(6)
	v_lshl_add_u32 v2, v15, 12, v2
	v_and_b32_e32 v3, 1, v14
	v_lshl_or_b32 v2, v3, 6, v2
	s_mov_b32 s61, 0
	v_cmp_eq_u32_e64 s[38:39], 0, v17
	v_cmp_gt_u32_e64 s[46:47], 16, v17
	v_or_b32_e32 v223, 16, v220
	v_or_b32_e32 v234, 32, v220
	v_or_b32_e32 v235, 48, v220
	v_or_b32_e32 v237, s25, v18
	v_and_or_b32 v238, v19, 24, s18
	v_mov_b32_e32 v209, v67
	v_lshl_add_u32 v210, v16, 1, v2
	v_mov_b32_e32 v211, v67
	s_barrier
	s_branch .LBB0_2406
